# PROJ GEMM leftover tiles (24 per XCD) split into 48 half tiles of 128 rows, both layers
# baseline (speedup 1.0000x reference)
.LBB0_215:
	s_mul_hi_i32 s0, s8, 0x2aaaaaab
	s_lshr_b32 s1, s0, 31
	s_ashr_i32 s0, s0, 5
	s_add_i32 s0, s0, s1
	s_lshl_b32 s1, s0, 3
	s_sub_i32 s2, 17, s1
	s_min_u32 s2, s2, 8
	v_cvt_f32_ubyte0_e32 v0, s2
	v_rcp_iflag_f32_e32 v0, v0
	s_sub_i32 s5, 0, s2
	s_mulk_i32 s0, 0xff40
	s_add_i32 s3, s0, s8
	v_mul_f32_e32 v0, 0x4f7ffffe, v0
	v_cvt_u32_f32_e32 v0, v0
	s_abs_i32 s4, s3
	s_ashr_i32 s0, s3, 31
	v_mov_b32_e32 v181, v179
	v_readfirstlane_b32 s6, v0
	s_mul_i32 s5, s5, s6
	s_mul_hi_u32 s5, s6, s5
	s_add_i32 s6, s6, s5
	s_mul_hi_u32 s5, s4, s6
	s_mul_i32 s6, s5, s2
	s_sub_i32 s4, s4, s6
	s_add_i32 s6, s5, 1
	s_sub_i32 s7, s4, s2
	s_cmp_ge_u32 s4, s2
	s_cselect_b32 s5, s6, s5
	s_cselect_b32 s4, s7, s4
	s_add_i32 s6, s5, 1
	s_cmp_ge_u32 s4, s2
	s_cselect_b32 s4, s6, s5
	s_xor_b32 s4, s4, s0
	s_sub_i32 s0, s4, s0
	s_mul_i32 s2, s2, s0
	s_sub_i32 s2, s3, s2
	s_add_i32 s1, s1, s11
	s_add_i32 s2, s1, s2
	v_ashrrev_i32_e32 v233, 6, v181
	v_lshlrev_b32_e32 v0, 1, v233
	v_lshl_add_u32 v0, s2, 3, v0
	v_ashrrev_i32_e32 v1, 31, v0
	v_bfe_u32 v183, v181, 5, 1
	v_lshlrev_b64 v[0:1], 16, v[0:1]
	v_and_b32_e32 v231, 31, v181
	v_lshl_add_u64 v[0:1], s[64:65], 0, v[0:1]
	v_lshlrev_b32_e32 v176, 9, v183
	s_ashr_i32 s1, s0, 31
	v_lshl_add_u64 v[0:1], v[0:1], 0, v[176:177]
	v_lshlrev_b32_e32 v176, 4, v231
	v_ashrrev_i32_e32 v12, 2, v181
	s_lshl_b64 s[4:5], s[0:1], 18
	v_lshl_add_u64 v[184:185], v[0:1], 0, v[176:177]
	s_add_u32 s4, s9, s4
	v_lshlrev_b32_e32 v0, 5, v12
	s_addc_u32 s5, s10, s5
	v_ashrrev_i32_e32 v1, 31, v0
	v_lshlrev_b32_e32 v2, 4, v181
	v_lshl_add_u64 v[0:1], v[0:1], 1, s[4:5]
	v_and_b32_e32 v176, 48, v2
	v_lshl_add_u64 v[186:187], v[0:1], 0, v[176:177]
	s_movk_i32 s1, 0x2000
	v_add_co_u32_e32 v8, vcc, s1, v186
	v_mul_u32_u24_e32 v10, 40, v231
	s_nop 0
	v_addc_co_u32_e32 v9, vcc, 0, v187, vcc
	v_lshlrev_b32_e32 v11, 4, v183
	v_lshl_add_u32 v235, v10, 1, v11
	v_add_co_u32_e32 v10, vcc, s41, v184
	s_movk_i32 s3, 0x50
	s_nop 0
	v_addc_co_u32_e32 v11, vcc, 0, v185, vcc
	v_and_b32_e32 v232, 63, v181
	v_lshlrev_b32_e32 v234, 3, v181
	s_cmp_eq_u32 s100, 1
	s_cbranch_scc1 .Lhx_proj_half
	v_bfe_u32 v197, v181, 4, 2
	v_lshlrev_b32_e32 v197, 1, v197
	v_mov_b32_e32 v176, 0x78
	v_lshrrev_b32_e32 v197, v197, v176
	v_and_b32_e32 v197, 3, v197
	v_and_b32_e32 v196, 3, v181
	v_xor_b32_e32 v197, v197, v196
	v_lshlrev_b32_e32 v197, 4, v197
	v_and_b32_e32 v188, 0xffffffcf, v186
	v_or_b32_e32 v188, v188, v197
	v_mov_b32_e32 v189, v187
	v_lshrrev_b32_e32 v176, 6, v181
	v_lshlrev_b32_e32 v197, 11, v176
	v_lshlrev_b32_e32 v176, 10, v176
	v_lshl_add_u64 v[188:189], v[188:189], 0, v[176:177]
	v_readfirstlane_b32 vcc_lo, v197
	v_bfe_u32 v197, v181, 4, 1
	v_lshlrev_b32_e32 v176, 9, v183
	v_lshl_add_u32 v176, v197, 8, v176
	v_lshl_add_u64 v[184:185], v[184:185], 0, v[176:177]
	v_mov_b32_e32 v176, s41
	v_lshl_add_u64 v[186:187], v[184:185], 0, v[176:177]
	v_mov_b32_e32 v176, 0x78
	v_bfe_u32 v197, v181, 2, 2
	v_lshlrev_b32_e32 v197, 1, v197
	v_lshrrev_b32_e32 v197, v197, v176
	v_and_b32_e32 v197, 3, v197
	v_bfe_u32 v196, v181, 4, 2
	v_xor_b32_e32 v197, v197, v196
	v_lshlrev_b32_e32 v197, 4, v197
	v_and_b32_e32 v196, 15, v181
	v_lshl_add_u32 v196, v196, 6, v197
	s_mov_b32 s96, 0
	s_mov_b32 m0, vcc_lo
	v_lshl_add_u64 v[160:161], v[188:189], 0, s[96:97]
	global_load_lds_dwordx4 v[160:161], off
	global_load_lds_dwordx4 v[160:161], off offset:1024
	s_mov_b32 s96, 0
	v_lshl_add_u64 v[198:199], v[184:185], 0, s[96:97]
	v_lshl_add_u64 v[200:201], v[186:187], 0, s[96:97]
	global_load_dwordx4 v[128:131], v[198:199], off
	global_load_dwordx4 v[132:135], v[198:199], off offset:256
	global_load_dwordx4 v[136:139], v[200:201], off
	global_load_dwordx4 v[140:143], v[200:201], off offset:256
	s_movk_i32 s96, 0x2000
	s_add_i32 m0, vcc_lo, 8192
	v_lshl_add_u64 v[160:161], v[188:189], 0, s[96:97]
	global_load_lds_dwordx4 v[160:161], off
	global_load_lds_dwordx4 v[160:161], off offset:1024
	s_movk_i32 s96, 0x800
	v_lshl_add_u64 v[198:199], v[184:185], 0, s[96:97]
	v_lshl_add_u64 v[200:201], v[186:187], 0, s[96:97]
	global_load_dwordx4 v[144:147], v[198:199], off
	global_load_dwordx4 v[148:151], v[198:199], off offset:256
	global_load_dwordx4 v[152:155], v[200:201], off
	global_load_dwordx4 v[156:159], v[200:201], off offset:256
	v_mov_b32_e32 v0, 0
	v_mov_b32_e32 v1, 0
	v_mov_b32_e32 v2, 0
	v_mov_b32_e32 v3, 0
	v_mov_b32_e32 v4, 0
	v_mov_b32_e32 v5, 0
	v_mov_b32_e32 v6, 0
	v_mov_b32_e32 v7, 0
	v_mov_b32_e32 v8, 0
	v_mov_b32_e32 v9, 0
	v_mov_b32_e32 v10, 0
	v_mov_b32_e32 v11, 0
	v_mov_b32_e32 v12, 0
	v_mov_b32_e32 v13, 0
	v_mov_b32_e32 v14, 0
	v_mov_b32_e32 v15, 0
	v_mov_b32_e32 v16, 0
	v_mov_b32_e32 v17, 0
	v_mov_b32_e32 v18, 0
	v_mov_b32_e32 v19, 0
	v_mov_b32_e32 v20, 0
	v_mov_b32_e32 v21, 0
	v_mov_b32_e32 v22, 0
	v_mov_b32_e32 v23, 0
	v_mov_b32_e32 v24, 0
	v_mov_b32_e32 v25, 0
	v_mov_b32_e32 v26, 0
	v_mov_b32_e32 v27, 0
	v_mov_b32_e32 v28, 0
	v_mov_b32_e32 v29, 0
	v_mov_b32_e32 v30, 0
	v_mov_b32_e32 v31, 0
	v_mov_b32_e32 v32, 0
	v_mov_b32_e32 v33, 0
	v_mov_b32_e32 v34, 0
	v_mov_b32_e32 v35, 0
	v_mov_b32_e32 v36, 0
	v_mov_b32_e32 v37, 0
	v_mov_b32_e32 v38, 0
	v_mov_b32_e32 v39, 0
	v_mov_b32_e32 v40, 0
	v_mov_b32_e32 v41, 0
	v_mov_b32_e32 v42, 0
	v_mov_b32_e32 v43, 0
	v_mov_b32_e32 v44, 0
	v_mov_b32_e32 v45, 0
	v_mov_b32_e32 v46, 0
	v_mov_b32_e32 v47, 0
	v_mov_b32_e32 v48, 0
	v_mov_b32_e32 v49, 0
	v_mov_b32_e32 v50, 0
	v_mov_b32_e32 v51, 0
	v_mov_b32_e32 v52, 0
	v_mov_b32_e32 v53, 0
	v_mov_b32_e32 v54, 0
	v_mov_b32_e32 v55, 0
	v_mov_b32_e32 v56, 0
	v_mov_b32_e32 v57, 0
	v_mov_b32_e32 v58, 0
	v_mov_b32_e32 v59, 0
	v_mov_b32_e32 v60, 0
	v_mov_b32_e32 v61, 0
	v_mov_b32_e32 v62, 0
	v_mov_b32_e32 v63, 0
	v_mov_b32_e32 v64, 0
	v_mov_b32_e32 v65, 0
	v_mov_b32_e32 v66, 0
	v_mov_b32_e32 v67, 0
	v_mov_b32_e32 v68, 0
	v_mov_b32_e32 v69, 0
	v_mov_b32_e32 v70, 0
	v_mov_b32_e32 v71, 0
	v_mov_b32_e32 v72, 0
	v_mov_b32_e32 v73, 0
	v_mov_b32_e32 v74, 0
	v_mov_b32_e32 v75, 0
	v_mov_b32_e32 v76, 0
	v_mov_b32_e32 v77, 0
	v_mov_b32_e32 v78, 0
	v_mov_b32_e32 v79, 0
	v_mov_b32_e32 v80, 0
	v_mov_b32_e32 v81, 0
	v_mov_b32_e32 v82, 0
	v_mov_b32_e32 v83, 0
	v_mov_b32_e32 v84, 0
	v_mov_b32_e32 v85, 0
	v_mov_b32_e32 v86, 0
	v_mov_b32_e32 v87, 0
	v_mov_b32_e32 v88, 0
	v_mov_b32_e32 v89, 0
	v_mov_b32_e32 v90, 0
	v_mov_b32_e32 v91, 0
	v_mov_b32_e32 v92, 0
	v_mov_b32_e32 v93, 0
	v_mov_b32_e32 v94, 0
	v_mov_b32_e32 v95, 0
	v_mov_b32_e32 v96, 0
	v_mov_b32_e32 v97, 0
	v_mov_b32_e32 v98, 0
	v_mov_b32_e32 v99, 0
	v_mov_b32_e32 v100, 0
	v_mov_b32_e32 v101, 0
	v_mov_b32_e32 v102, 0
	v_mov_b32_e32 v103, 0
	v_mov_b32_e32 v104, 0
	v_mov_b32_e32 v105, 0
	v_mov_b32_e32 v106, 0
	v_mov_b32_e32 v107, 0
	v_mov_b32_e32 v108, 0
	v_mov_b32_e32 v109, 0
	v_mov_b32_e32 v110, 0
	v_mov_b32_e32 v111, 0
	v_mov_b32_e32 v112, 0
	v_mov_b32_e32 v113, 0
	v_mov_b32_e32 v114, 0
	v_mov_b32_e32 v115, 0
	v_mov_b32_e32 v116, 0
	v_mov_b32_e32 v117, 0
	v_mov_b32_e32 v118, 0
	v_mov_b32_e32 v119, 0
	v_mov_b32_e32 v120, 0
	v_mov_b32_e32 v121, 0
	v_mov_b32_e32 v122, 0
	v_mov_b32_e32 v123, 0
	v_mov_b32_e32 v124, 0
	v_mov_b32_e32 v125, 0
	v_mov_b32_e32 v126, 0
	v_mov_b32_e32 v127, 0
	s_mov_b32 s1, 0
	s_waitcnt vmcnt(4)
	s_barrier

.Lpe_proj_end:
	v_readlane_b32 s16, v254, 11
	s_add_i32 s8, s8, s16
	s_cmpk_lt_i32 s8, 0x180
	s_cbranch_scc0 .Lhx_proj_left
	s_barrier
	s_branch .LBB0_215
.Lhx_proj_left:
	v_readlane_b32 s19, v253, 0
	s_ashr_i32 s19, s19, 3
	s_cmp_lt_i32 s19, 48
	s_cbranch_scc0 .Lhx_proj_done
	s_mov_b32 s100, 1
	s_and_b32 s101, s19, 1
	s_lshr_b32 s19, s19, 1
	s_add_i32 s8, s19, 0x180
	s_barrier
	s_branch .LBB0_215

.Lhx_proj_half:
	v_bfe_u32 v197, v181, 4, 2
	v_lshlrev_b32_e32 v197, 1, v197
	v_mov_b32_e32 v176, 0x78
	v_lshrrev_b32_e32 v197, v197, v176
	v_and_b32_e32 v197, 3, v197
	v_and_b32_e32 v196, 3, v181
	v_xor_b32_e32 v197, v197, v196
	v_lshlrev_b32_e32 v197, 4, v197
	v_and_b32_e32 v188, 0xffffffcf, v186
	v_or_b32_e32 v188, v188, v197
	v_mov_b32_e32 v189, v187
	v_lshrrev_b32_e32 v176, 6, v181
	v_lshlrev_b32_e32 v197, 11, v176
	v_lshlrev_b32_e32 v176, 10, v176
	v_lshl_add_u64 v[188:189], v[188:189], 0, v[176:177]
	v_readfirstlane_b32 vcc_lo, v197
	v_bfe_u32 v197, v181, 4, 1
	v_lshlrev_b32_e32 v176, 9, v183
	v_lshl_add_u32 v176, v197, 8, v176
	v_lshl_add_u64 v[184:185], v[184:185], 0, v[176:177]
	v_mov_b32_e32 v176, s41
	v_lshl_add_u64 v[186:187], v[184:185], 0, v[176:177]
	v_mov_b32_e32 v176, 0x78
	v_bfe_u32 v197, v181, 2, 2
	v_lshlrev_b32_e32 v197, 1, v197
	v_lshrrev_b32_e32 v197, v197, v176
	v_and_b32_e32 v197, 3, v197
	v_bfe_u32 v196, v181, 4, 2
	v_xor_b32_e32 v197, v197, v196
	v_lshlrev_b32_e32 v197, 4, v197
	v_and_b32_e32 v196, 15, v181
	v_lshl_add_u32 v196, v196, 6, v197
	s_cmp_eq_u32 s101, 1
	s_cbranch_scc0 .Lg16_projh_a0
	v_mov_b32_e32 v184, v186
	v_mov_b32_e32 v185, v187
.Lg16_projh_a0:
	s_mov_b32 s96, 0
	s_mov_b32 m0, vcc_lo
	v_lshl_add_u64 v[160:161], v[188:189], 0, s[96:97]
	global_load_lds_dwordx4 v[160:161], off
	global_load_lds_dwordx4 v[160:161], off offset:1024
	s_mov_b32 s96, 0
	v_lshl_add_u64 v[198:199], v[184:185], 0, s[96:97]
	v_lshl_add_u64 v[200:201], v[186:187], 0, s[96:97]
	global_load_dwordx4 v[128:131], v[198:199], off
	global_load_dwordx4 v[132:135], v[198:199], off offset:256
	s_movk_i32 s96, 0x2000
	s_add_i32 m0, vcc_lo, 8192
	v_lshl_add_u64 v[160:161], v[188:189], 0, s[96:97]
	global_load_lds_dwordx4 v[160:161], off
	global_load_lds_dwordx4 v[160:161], off offset:1024
	s_movk_i32 s96, 0x800
	v_lshl_add_u64 v[198:199], v[184:185], 0, s[96:97]
	v_lshl_add_u64 v[200:201], v[186:187], 0, s[96:97]
	global_load_dwordx4 v[144:147], v[198:199], off
	global_load_dwordx4 v[148:151], v[198:199], off offset:256
	v_mov_b32_e32 v0, 0
	v_mov_b32_e32 v1, 0
	v_mov_b32_e32 v2, 0
	v_mov_b32_e32 v3, 0
	v_mov_b32_e32 v4, 0
	v_mov_b32_e32 v5, 0
	v_mov_b32_e32 v6, 0
	v_mov_b32_e32 v7, 0
	v_mov_b32_e32 v8, 0
	v_mov_b32_e32 v9, 0
	v_mov_b32_e32 v10, 0
	v_mov_b32_e32 v11, 0
	v_mov_b32_e32 v12, 0
	v_mov_b32_e32 v13, 0
	v_mov_b32_e32 v14, 0
	v_mov_b32_e32 v15, 0
	v_mov_b32_e32 v16, 0
	v_mov_b32_e32 v17, 0
	v_mov_b32_e32 v18, 0
	v_mov_b32_e32 v19, 0
	v_mov_b32_e32 v20, 0
	v_mov_b32_e32 v21, 0
	v_mov_b32_e32 v22, 0
	v_mov_b32_e32 v23, 0
	v_mov_b32_e32 v24, 0
	v_mov_b32_e32 v25, 0
	v_mov_b32_e32 v26, 0
	v_mov_b32_e32 v27, 0
	v_mov_b32_e32 v28, 0
	v_mov_b32_e32 v29, 0
	v_mov_b32_e32 v30, 0
	v_mov_b32_e32 v31, 0
	v_mov_b32_e32 v32, 0
	v_mov_b32_e32 v33, 0
	v_mov_b32_e32 v34, 0
	v_mov_b32_e32 v35, 0
	v_mov_b32_e32 v36, 0
	v_mov_b32_e32 v37, 0
	v_mov_b32_e32 v38, 0
	v_mov_b32_e32 v39, 0
	v_mov_b32_e32 v40, 0
	v_mov_b32_e32 v41, 0
	v_mov_b32_e32 v42, 0
	v_mov_b32_e32 v43, 0
	v_mov_b32_e32 v44, 0
	v_mov_b32_e32 v45, 0
	v_mov_b32_e32 v46, 0
	v_mov_b32_e32 v47, 0
	v_mov_b32_e32 v48, 0
	v_mov_b32_e32 v49, 0
	v_mov_b32_e32 v50, 0
	v_mov_b32_e32 v51, 0
	v_mov_b32_e32 v52, 0
	v_mov_b32_e32 v53, 0
	v_mov_b32_e32 v54, 0
	v_mov_b32_e32 v55, 0
	v_mov_b32_e32 v56, 0
	v_mov_b32_e32 v57, 0
	v_mov_b32_e32 v58, 0
	v_mov_b32_e32 v59, 0
	v_mov_b32_e32 v60, 0
	v_mov_b32_e32 v61, 0
	v_mov_b32_e32 v62, 0
	v_mov_b32_e32 v63, 0
	v_mov_b32_e32 v64, 0
	v_mov_b32_e32 v65, 0
	v_mov_b32_e32 v66, 0
	v_mov_b32_e32 v67, 0
	v_mov_b32_e32 v68, 0
	v_mov_b32_e32 v69, 0
	v_mov_b32_e32 v70, 0
	v_mov_b32_e32 v71, 0
	v_mov_b32_e32 v72, 0
	v_mov_b32_e32 v73, 0
	v_mov_b32_e32 v74, 0
	v_mov_b32_e32 v75, 0
	v_mov_b32_e32 v76, 0
	v_mov_b32_e32 v77, 0
	v_mov_b32_e32 v78, 0
	v_mov_b32_e32 v79, 0
	v_mov_b32_e32 v80, 0
	v_mov_b32_e32 v81, 0
	v_mov_b32_e32 v82, 0
	v_mov_b32_e32 v83, 0
	v_mov_b32_e32 v84, 0
	v_mov_b32_e32 v85, 0
	v_mov_b32_e32 v86, 0
	v_mov_b32_e32 v87, 0
	v_mov_b32_e32 v88, 0
	v_mov_b32_e32 v89, 0
	v_mov_b32_e32 v90, 0
	v_mov_b32_e32 v91, 0
	v_mov_b32_e32 v92, 0
	v_mov_b32_e32 v93, 0
	v_mov_b32_e32 v94, 0
	v_mov_b32_e32 v95, 0
	v_mov_b32_e32 v96, 0
	v_mov_b32_e32 v97, 0
	v_mov_b32_e32 v98, 0
	v_mov_b32_e32 v99, 0
	v_mov_b32_e32 v100, 0
	v_mov_b32_e32 v101, 0
	v_mov_b32_e32 v102, 0
	v_mov_b32_e32 v103, 0
	v_mov_b32_e32 v104, 0
	v_mov_b32_e32 v105, 0
	v_mov_b32_e32 v106, 0
	v_mov_b32_e32 v107, 0
	v_mov_b32_e32 v108, 0
	v_mov_b32_e32 v109, 0
	v_mov_b32_e32 v110, 0
	v_mov_b32_e32 v111, 0
	v_mov_b32_e32 v112, 0
	v_mov_b32_e32 v113, 0
	v_mov_b32_e32 v114, 0
	v_mov_b32_e32 v115, 0
	v_mov_b32_e32 v116, 0
	v_mov_b32_e32 v117, 0
	v_mov_b32_e32 v118, 0
	v_mov_b32_e32 v119, 0
	v_mov_b32_e32 v120, 0
	v_mov_b32_e32 v121, 0
	v_mov_b32_e32 v122, 0
	v_mov_b32_e32 v123, 0
	v_mov_b32_e32 v124, 0
	v_mov_b32_e32 v125, 0
	v_mov_b32_e32 v126, 0
	v_mov_b32_e32 v127, 0
	s_mov_b32 s1, 0
	s_waitcnt vmcnt(2)
	s_barrier
.Lg16_projh_k:
	s_add_i32 s3, s1, 2
	s_lshl_b32 s96, s3, 13
	s_add_i32 m0, vcc_lo, 16384
	v_lshl_add_u64 v[160:161], v[188:189], 0, s[96:97]
	global_load_lds_dwordx4 v[160:161], off
	global_load_lds_dwordx4 v[160:161], off offset:1024
	ds_read_b128 v[236:239], v196 offset:0
	ds_read_b128 v[240:243], v196 offset:1024
	ds_read_b128 v[244:247], v196 offset:2048
	ds_read_b128 v[248:251], v196 offset:3072
	s_add_i32 s3, s1, 2
	s_lshl_b32 s96, s3, 11
	v_lshl_add_u64 v[198:199], v[184:185], 0, s[96:97]
	v_lshl_add_u64 v[200:201], v[186:187], 0, s[96:97]
	s_waitcnt vmcnt(6) lgkmcnt(3)
	v_mfma_f32_16x16x32_bf16 v[16:19], v[128:131], v[236:239], v[16:19]
	v_mfma_f32_16x16x32_bf16 v[24:27], v[132:135], v[236:239], v[24:27]
	ds_read_b128 v[236:239], v196 offset:4096
	s_waitcnt lgkmcnt(3)
	v_mfma_f32_16x16x32_bf16 v[20:23], v[128:131], v[240:243], v[20:23]
	v_mfma_f32_16x16x32_bf16 v[28:31], v[132:135], v[240:243], v[28:31]
	ds_read_b128 v[240:243], v196 offset:5120
	s_waitcnt lgkmcnt(3)
	v_mfma_f32_16x16x32_bf16 v[112:115], v[128:131], v[244:247], v[112:115]
	v_mfma_f32_16x16x32_bf16 v[120:123], v[132:135], v[244:247], v[120:123]
	ds_read_b128 v[244:247], v196 offset:6144
	s_waitcnt lgkmcnt(3)
	v_mfma_f32_16x16x32_bf16 v[116:119], v[128:131], v[248:251], v[116:119]
	v_mfma_f32_16x16x32_bf16 v[124:127], v[132:135], v[248:251], v[124:127]
	ds_read_b128 v[248:251], v196 offset:7168
	s_waitcnt lgkmcnt(3)
	v_mfma_f32_16x16x32_bf16 v[80:83], v[128:131], v[236:239], v[80:83]
	v_mfma_f32_16x16x32_bf16 v[88:91], v[132:135], v[236:239], v[88:91]
	s_waitcnt lgkmcnt(2)
	v_mfma_f32_16x16x32_bf16 v[84:87], v[128:131], v[240:243], v[84:87]
	v_mfma_f32_16x16x32_bf16 v[92:95], v[132:135], v[240:243], v[92:95]
	s_waitcnt lgkmcnt(1)
	v_mfma_f32_16x16x32_bf16 v[64:67], v[128:131], v[244:247], v[64:67]
	v_mfma_f32_16x16x32_bf16 v[72:75], v[132:135], v[244:247], v[72:75]
	s_waitcnt lgkmcnt(0)
	v_mfma_f32_16x16x32_bf16 v[68:71], v[128:131], v[248:251], v[68:71]
	v_mfma_f32_16x16x32_bf16 v[76:79], v[132:135], v[248:251], v[76:79]
	global_load_dwordx4 v[128:131], v[198:199], off
	global_load_dwordx4 v[132:135], v[198:199], off offset:256
	s_waitcnt vmcnt(6)
	s_barrier
	s_add_i32 s3, s1, 3
	s_lshl_b32 s96, s3, 13
	s_mov_b32 m0, vcc_lo
	v_lshl_add_u64 v[160:161], v[188:189], 0, s[96:97]
	global_load_lds_dwordx4 v[160:161], off
	global_load_lds_dwordx4 v[160:161], off offset:1024
	ds_read_b128 v[236:239], v196 offset:8192
	ds_read_b128 v[240:243], v196 offset:9216
	ds_read_b128 v[244:247], v196 offset:10240
	ds_read_b128 v[248:251], v196 offset:11264
	s_add_i32 s3, s1, 3
	s_lshl_b32 s96, s3, 11
	v_lshl_add_u64 v[198:199], v[184:185], 0, s[96:97]
	v_lshl_add_u64 v[200:201], v[186:187], 0, s[96:97]
	s_waitcnt vmcnt(6) lgkmcnt(3)
	v_mfma_f32_16x16x32_bf16 v[16:19], v[144:147], v[236:239], v[16:19]
	v_mfma_f32_16x16x32_bf16 v[24:27], v[148:151], v[236:239], v[24:27]
	ds_read_b128 v[236:239], v196 offset:12288
	s_waitcnt lgkmcnt(3)
	v_mfma_f32_16x16x32_bf16 v[20:23], v[144:147], v[240:243], v[20:23]
	v_mfma_f32_16x16x32_bf16 v[28:31], v[148:151], v[240:243], v[28:31]
	ds_read_b128 v[240:243], v196 offset:13312
	s_waitcnt lgkmcnt(3)
	v_mfma_f32_16x16x32_bf16 v[112:115], v[144:147], v[244:247], v[112:115]
	v_mfma_f32_16x16x32_bf16 v[120:123], v[148:151], v[244:247], v[120:123]
	ds_read_b128 v[244:247], v196 offset:14336
	s_waitcnt lgkmcnt(3)
	v_mfma_f32_16x16x32_bf16 v[116:119], v[144:147], v[248:251], v[116:119]
	v_mfma_f32_16x16x32_bf16 v[124:127], v[148:151], v[248:251], v[124:127]
	ds_read_b128 v[248:251], v196 offset:15360
	s_waitcnt lgkmcnt(3)
	v_mfma_f32_16x16x32_bf16 v[80:83], v[144:147], v[236:239], v[80:83]
	v_mfma_f32_16x16x32_bf16 v[88:91], v[148:151], v[236:239], v[88:91]
	s_waitcnt lgkmcnt(2)
	v_mfma_f32_16x16x32_bf16 v[84:87], v[144:147], v[240:243], v[84:87]
	v_mfma_f32_16x16x32_bf16 v[92:95], v[148:151], v[240:243], v[92:95]
	s_waitcnt lgkmcnt(1)
	v_mfma_f32_16x16x32_bf16 v[64:67], v[144:147], v[244:247], v[64:67]
	v_mfma_f32_16x16x32_bf16 v[72:75], v[148:151], v[244:247], v[72:75]
	s_waitcnt lgkmcnt(0)
	v_mfma_f32_16x16x32_bf16 v[68:71], v[144:147], v[248:251], v[68:71]
	v_mfma_f32_16x16x32_bf16 v[76:79], v[148:151], v[248:251], v[76:79]
	global_load_dwordx4 v[144:147], v[198:199], off
	global_load_dwordx4 v[148:151], v[198:199], off offset:256
	s_waitcnt vmcnt(6)
	s_barrier
	s_add_i32 s3, s1, 4
	s_lshl_b32 s96, s3, 13
	s_add_i32 m0, vcc_lo, 8192
	v_lshl_add_u64 v[160:161], v[188:189], 0, s[96:97]
	global_load_lds_dwordx4 v[160:161], off
	global_load_lds_dwordx4 v[160:161], off offset:1024
	ds_read_b128 v[236:239], v196 offset:16384
	ds_read_b128 v[240:243], v196 offset:17408
	ds_read_b128 v[244:247], v196 offset:18432
	ds_read_b128 v[248:251], v196 offset:19456
	s_add_i32 s3, s1, 4
	s_lshl_b32 s96, s3, 11
	v_lshl_add_u64 v[198:199], v[184:185], 0, s[96:97]
	v_lshl_add_u64 v[200:201], v[186:187], 0, s[96:97]
	s_waitcnt vmcnt(6) lgkmcnt(3)
	v_mfma_f32_16x16x32_bf16 v[16:19], v[128:131], v[236:239], v[16:19]
	v_mfma_f32_16x16x32_bf16 v[24:27], v[132:135], v[236:239], v[24:27]
	ds_read_b128 v[236:239], v196 offset:20480
	s_waitcnt lgkmcnt(3)
	v_mfma_f32_16x16x32_bf16 v[20:23], v[128:131], v[240:243], v[20:23]
	v_mfma_f32_16x16x32_bf16 v[28:31], v[132:135], v[240:243], v[28:31]
	ds_read_b128 v[240:243], v196 offset:21504
	s_waitcnt lgkmcnt(3)
	v_mfma_f32_16x16x32_bf16 v[112:115], v[128:131], v[244:247], v[112:115]
	v_mfma_f32_16x16x32_bf16 v[120:123], v[132:135], v[244:247], v[120:123]
	ds_read_b128 v[244:247], v196 offset:22528
	s_waitcnt lgkmcnt(3)
	v_mfma_f32_16x16x32_bf16 v[116:119], v[128:131], v[248:251], v[116:119]
	v_mfma_f32_16x16x32_bf16 v[124:127], v[132:135], v[248:251], v[124:127]
	ds_read_b128 v[248:251], v196 offset:23552
	s_waitcnt lgkmcnt(3)
	v_mfma_f32_16x16x32_bf16 v[80:83], v[128:131], v[236:239], v[80:83]
	v_mfma_f32_16x16x32_bf16 v[88:91], v[132:135], v[236:239], v[88:91]
	s_waitcnt lgkmcnt(2)
	v_mfma_f32_16x16x32_bf16 v[84:87], v[128:131], v[240:243], v[84:87]
	v_mfma_f32_16x16x32_bf16 v[92:95], v[132:135], v[240:243], v[92:95]
	s_waitcnt lgkmcnt(1)
	v_mfma_f32_16x16x32_bf16 v[64:67], v[128:131], v[244:247], v[64:67]
	v_mfma_f32_16x16x32_bf16 v[72:75], v[132:135], v[244:247], v[72:75]
	s_waitcnt lgkmcnt(0)
	v_mfma_f32_16x16x32_bf16 v[68:71], v[128:131], v[248:251], v[68:71]
	v_mfma_f32_16x16x32_bf16 v[76:79], v[132:135], v[248:251], v[76:79]
	global_load_dwordx4 v[128:131], v[198:199], off
	global_load_dwordx4 v[132:135], v[198:199], off offset:256
	s_waitcnt vmcnt(6)
	s_barrier
	s_add_i32 s3, s1, 5
	s_lshl_b32 s96, s3, 13
	s_add_i32 m0, vcc_lo, 16384
	v_lshl_add_u64 v[160:161], v[188:189], 0, s[96:97]
	global_load_lds_dwordx4 v[160:161], off
	global_load_lds_dwordx4 v[160:161], off offset:1024
	ds_read_b128 v[236:239], v196 offset:0
	ds_read_b128 v[240:243], v196 offset:1024
	ds_read_b128 v[244:247], v196 offset:2048
	ds_read_b128 v[248:251], v196 offset:3072
	s_add_i32 s3, s1, 5
	s_lshl_b32 s96, s3, 11
	v_lshl_add_u64 v[198:199], v[184:185], 0, s[96:97]
	v_lshl_add_u64 v[200:201], v[186:187], 0, s[96:97]
	s_waitcnt vmcnt(6) lgkmcnt(3)
	v_mfma_f32_16x16x32_bf16 v[16:19], v[144:147], v[236:239], v[16:19]
	v_mfma_f32_16x16x32_bf16 v[24:27], v[148:151], v[236:239], v[24:27]
	ds_read_b128 v[236:239], v196 offset:4096
	s_waitcnt lgkmcnt(3)
	v_mfma_f32_16x16x32_bf16 v[20:23], v[144:147], v[240:243], v[20:23]
	v_mfma_f32_16x16x32_bf16 v[28:31], v[148:151], v[240:243], v[28:31]
	ds_read_b128 v[240:243], v196 offset:5120
	s_waitcnt lgkmcnt(3)
	v_mfma_f32_16x16x32_bf16 v[112:115], v[144:147], v[244:247], v[112:115]
	v_mfma_f32_16x16x32_bf16 v[120:123], v[148:151], v[244:247], v[120:123]
	ds_read_b128 v[244:247], v196 offset:6144
	s_waitcnt lgkmcnt(3)
	v_mfma_f32_16x16x32_bf16 v[116:119], v[144:147], v[248:251], v[116:119]
	v_mfma_f32_16x16x32_bf16 v[124:127], v[148:151], v[248:251], v[124:127]
	ds_read_b128 v[248:251], v196 offset:7168
	s_waitcnt lgkmcnt(3)
	v_mfma_f32_16x16x32_bf16 v[80:83], v[144:147], v[236:239], v[80:83]
	v_mfma_f32_16x16x32_bf16 v[88:91], v[148:151], v[236:239], v[88:91]
	s_waitcnt lgkmcnt(2)
	v_mfma_f32_16x16x32_bf16 v[84:87], v[144:147], v[240:243], v[84:87]
	v_mfma_f32_16x16x32_bf16 v[92:95], v[148:151], v[240:243], v[92:95]
	s_waitcnt lgkmcnt(1)
	v_mfma_f32_16x16x32_bf16 v[64:67], v[144:147], v[244:247], v[64:67]
	v_mfma_f32_16x16x32_bf16 v[72:75], v[148:151], v[244:247], v[72:75]
	s_waitcnt lgkmcnt(0)
	v_mfma_f32_16x16x32_bf16 v[68:71], v[144:147], v[248:251], v[68:71]
	v_mfma_f32_16x16x32_bf16 v[76:79], v[148:151], v[248:251], v[76:79]
	global_load_dwordx4 v[144:147], v[198:199], off
	global_load_dwordx4 v[148:151], v[198:199], off offset:256
	s_waitcnt vmcnt(6)
	s_barrier
	s_add_i32 s3, s1, 6
	s_lshl_b32 s96, s3, 13
	s_mov_b32 m0, vcc_lo
	v_lshl_add_u64 v[160:161], v[188:189], 0, s[96:97]
	global_load_lds_dwordx4 v[160:161], off
	global_load_lds_dwordx4 v[160:161], off offset:1024
	ds_read_b128 v[236:239], v196 offset:8192
	ds_read_b128 v[240:243], v196 offset:9216
	ds_read_b128 v[244:247], v196 offset:10240
	ds_read_b128 v[248:251], v196 offset:11264
	s_add_i32 s3, s1, 6
	s_lshl_b32 s96, s3, 11
	v_lshl_add_u64 v[198:199], v[184:185], 0, s[96:97]
	v_lshl_add_u64 v[200:201], v[186:187], 0, s[96:97]
	s_waitcnt vmcnt(6) lgkmcnt(3)
	v_mfma_f32_16x16x32_bf16 v[16:19], v[128:131], v[236:239], v[16:19]
	v_mfma_f32_16x16x32_bf16 v[24:27], v[132:135], v[236:239], v[24:27]
	ds_read_b128 v[236:239], v196 offset:12288
	s_waitcnt lgkmcnt(3)
	v_mfma_f32_16x16x32_bf16 v[20:23], v[128:131], v[240:243], v[20:23]
	v_mfma_f32_16x16x32_bf16 v[28:31], v[132:135], v[240:243], v[28:31]
	ds_read_b128 v[240:243], v196 offset:13312
	s_waitcnt lgkmcnt(3)
	v_mfma_f32_16x16x32_bf16 v[112:115], v[128:131], v[244:247], v[112:115]
	v_mfma_f32_16x16x32_bf16 v[120:123], v[132:135], v[244:247], v[120:123]
	ds_read_b128 v[244:247], v196 offset:14336
	s_waitcnt lgkmcnt(3)
	v_mfma_f32_16x16x32_bf16 v[116:119], v[128:131], v[248:251], v[116:119]
	v_mfma_f32_16x16x32_bf16 v[124:127], v[132:135], v[248:251], v[124:127]
	ds_read_b128 v[248:251], v196 offset:15360
	s_waitcnt lgkmcnt(3)
	v_mfma_f32_16x16x32_bf16 v[80:83], v[128:131], v[236:239], v[80:83]
	v_mfma_f32_16x16x32_bf16 v[88:91], v[132:135], v[236:239], v[88:91]
	s_waitcnt lgkmcnt(2)
	v_mfma_f32_16x16x32_bf16 v[84:87], v[128:131], v[240:243], v[84:87]
	v_mfma_f32_16x16x32_bf16 v[92:95], v[132:135], v[240:243], v[92:95]
	s_waitcnt lgkmcnt(1)
	v_mfma_f32_16x16x32_bf16 v[64:67], v[128:131], v[244:247], v[64:67]
	v_mfma_f32_16x16x32_bf16 v[72:75], v[132:135], v[244:247], v[72:75]
	s_waitcnt lgkmcnt(0)
	v_mfma_f32_16x16x32_bf16 v[68:71], v[128:131], v[248:251], v[68:71]
	v_mfma_f32_16x16x32_bf16 v[76:79], v[132:135], v[248:251], v[76:79]
	global_load_dwordx4 v[128:131], v[198:199], off
	global_load_dwordx4 v[132:135], v[198:199], off offset:256
	s_waitcnt vmcnt(6)
	s_barrier
	s_add_i32 s3, s1, 7
	s_lshl_b32 s96, s3, 13
	s_add_i32 m0, vcc_lo, 8192
	v_lshl_add_u64 v[160:161], v[188:189], 0, s[96:97]
	global_load_lds_dwordx4 v[160:161], off
	global_load_lds_dwordx4 v[160:161], off offset:1024
	ds_read_b128 v[236:239], v196 offset:16384
	ds_read_b128 v[240:243], v196 offset:17408
	ds_read_b128 v[244:247], v196 offset:18432
	ds_read_b128 v[248:251], v196 offset:19456
	s_add_i32 s3, s1, 7
	s_lshl_b32 s96, s3, 11
	v_lshl_add_u64 v[198:199], v[184:185], 0, s[96:97]
	v_lshl_add_u64 v[200:201], v[186:187], 0, s[96:97]
	s_waitcnt vmcnt(6) lgkmcnt(3)
	v_mfma_f32_16x16x32_bf16 v[16:19], v[144:147], v[236:239], v[16:19]
	v_mfma_f32_16x16x32_bf16 v[24:27], v[148:151], v[236:239], v[24:27]
	ds_read_b128 v[236:239], v196 offset:20480
	s_waitcnt lgkmcnt(3)
	v_mfma_f32_16x16x32_bf16 v[20:23], v[144:147], v[240:243], v[20:23]
	v_mfma_f32_16x16x32_bf16 v[28:31], v[148:151], v[240:243], v[28:31]
	ds_read_b128 v[240:243], v196 offset:21504
	s_waitcnt lgkmcnt(3)
	v_mfma_f32_16x16x32_bf16 v[112:115], v[144:147], v[244:247], v[112:115]
	v_mfma_f32_16x16x32_bf16 v[120:123], v[148:151], v[244:247], v[120:123]
	ds_read_b128 v[244:247], v196 offset:22528
	s_waitcnt lgkmcnt(3)
	v_mfma_f32_16x16x32_bf16 v[116:119], v[144:147], v[248:251], v[116:119]
	v_mfma_f32_16x16x32_bf16 v[124:127], v[148:151], v[248:251], v[124:127]
	ds_read_b128 v[248:251], v196 offset:23552
	s_waitcnt lgkmcnt(3)
	v_mfma_f32_16x16x32_bf16 v[80:83], v[144:147], v[236:239], v[80:83]
	v_mfma_f32_16x16x32_bf16 v[88:91], v[148:151], v[236:239], v[88:91]
	s_waitcnt lgkmcnt(2)
	v_mfma_f32_16x16x32_bf16 v[84:87], v[144:147], v[240:243], v[84:87]
	v_mfma_f32_16x16x32_bf16 v[92:95], v[148:151], v[240:243], v[92:95]
	s_waitcnt lgkmcnt(1)
	v_mfma_f32_16x16x32_bf16 v[64:67], v[144:147], v[244:247], v[64:67]
	v_mfma_f32_16x16x32_bf16 v[72:75], v[148:151], v[244:247], v[72:75]
	s_waitcnt lgkmcnt(0)
	v_mfma_f32_16x16x32_bf16 v[68:71], v[144:147], v[248:251], v[68:71]
	v_mfma_f32_16x16x32_bf16 v[76:79], v[148:151], v[248:251], v[76:79]
	global_load_dwordx4 v[144:147], v[198:199], off
	global_load_dwordx4 v[148:151], v[198:199], off offset:256
	s_waitcnt vmcnt(6)
	s_barrier
	s_add_i32 s1, s1, 6
	s_cmp_lt_u32 s1, 30
	s_cbranch_scc1 .Lg16_projh_k
	ds_read_b128 v[236:239], v196 offset:0
	ds_read_b128 v[240:243], v196 offset:1024
	ds_read_b128 v[244:247], v196 offset:2048
	ds_read_b128 v[248:251], v196 offset:3072
	s_waitcnt vmcnt(4) lgkmcnt(3)
	v_mfma_f32_16x16x32_bf16 v[16:19], v[128:131], v[236:239], v[16:19]
	v_mfma_f32_16x16x32_bf16 v[24:27], v[132:135], v[236:239], v[24:27]
	ds_read_b128 v[236:239], v196 offset:4096
	s_waitcnt lgkmcnt(3)
	v_mfma_f32_16x16x32_bf16 v[20:23], v[128:131], v[240:243], v[20:23]
	v_mfma_f32_16x16x32_bf16 v[28:31], v[132:135], v[240:243], v[28:31]
	ds_read_b128 v[240:243], v196 offset:5120
	s_waitcnt lgkmcnt(3)
	v_mfma_f32_16x16x32_bf16 v[112:115], v[128:131], v[244:247], v[112:115]
	v_mfma_f32_16x16x32_bf16 v[120:123], v[132:135], v[244:247], v[120:123]
	ds_read_b128 v[244:247], v196 offset:6144
	s_waitcnt lgkmcnt(3)
	v_mfma_f32_16x16x32_bf16 v[116:119], v[128:131], v[248:251], v[116:119]
	v_mfma_f32_16x16x32_bf16 v[124:127], v[132:135], v[248:251], v[124:127]
	ds_read_b128 v[248:251], v196 offset:7168
	s_waitcnt lgkmcnt(3)
	v_mfma_f32_16x16x32_bf16 v[80:83], v[128:131], v[236:239], v[80:83]
	v_mfma_f32_16x16x32_bf16 v[88:91], v[132:135], v[236:239], v[88:91]
	s_waitcnt lgkmcnt(2)
	v_mfma_f32_16x16x32_bf16 v[84:87], v[128:131], v[240:243], v[84:87]
	v_mfma_f32_16x16x32_bf16 v[92:95], v[132:135], v[240:243], v[92:95]
	s_waitcnt lgkmcnt(1)
	v_mfma_f32_16x16x32_bf16 v[64:67], v[128:131], v[244:247], v[64:67]
	v_mfma_f32_16x16x32_bf16 v[72:75], v[132:135], v[244:247], v[72:75]
	s_waitcnt lgkmcnt(0)
	v_mfma_f32_16x16x32_bf16 v[68:71], v[128:131], v[248:251], v[68:71]
	v_mfma_f32_16x16x32_bf16 v[76:79], v[132:135], v[248:251], v[76:79]
	s_waitcnt vmcnt(2)
	s_barrier
	ds_read_b128 v[236:239], v196 offset:8192
	ds_read_b128 v[240:243], v196 offset:9216
	ds_read_b128 v[244:247], v196 offset:10240
	ds_read_b128 v[248:251], v196 offset:11264
	s_waitcnt vmcnt(0) lgkmcnt(3)
	v_mfma_f32_16x16x32_bf16 v[16:19], v[144:147], v[236:239], v[16:19]
	v_mfma_f32_16x16x32_bf16 v[24:27], v[148:151], v[236:239], v[24:27]
	ds_read_b128 v[236:239], v196 offset:12288
	s_waitcnt lgkmcnt(3)
	v_mfma_f32_16x16x32_bf16 v[20:23], v[144:147], v[240:243], v[20:23]
	v_mfma_f32_16x16x32_bf16 v[28:31], v[148:151], v[240:243], v[28:31]
	ds_read_b128 v[240:243], v196 offset:13312
	s_waitcnt lgkmcnt(3)
	v_mfma_f32_16x16x32_bf16 v[112:115], v[144:147], v[244:247], v[112:115]
	v_mfma_f32_16x16x32_bf16 v[120:123], v[148:151], v[244:247], v[120:123]
	ds_read_b128 v[244:247], v196 offset:14336
	s_waitcnt lgkmcnt(3)
	v_mfma_f32_16x16x32_bf16 v[116:119], v[144:147], v[248:251], v[116:119]
	v_mfma_f32_16x16x32_bf16 v[124:127], v[148:151], v[248:251], v[124:127]
	ds_read_b128 v[248:251], v196 offset:15360
	v_permlane16_swap_b32_e32 v16, v20
	v_permlane16_swap_b32_e32 v17, v21
	v_permlane16_swap_b32_e32 v18, v22
	v_permlane16_swap_b32_e32 v19, v23
	v_permlane16_swap_b32_e32 v24, v28
	v_permlane16_swap_b32_e32 v25, v29
	v_permlane16_swap_b32_e32 v26, v30
	v_permlane16_swap_b32_e32 v27, v31
	v_permlane16_swap_b32_e32 v0, v4
	v_permlane16_swap_b32_e32 v1, v5
	v_permlane16_swap_b32_e32 v2, v6
	v_permlane16_swap_b32_e32 v3, v7
	v_permlane16_swap_b32_e32 v8, v12
	v_permlane16_swap_b32_e32 v9, v13
	v_permlane16_swap_b32_e32 v10, v14
	v_permlane16_swap_b32_e32 v11, v15
	v_permlane32_swap_b32_e32 v16, v20
	v_permlane32_swap_b32_e32 v17, v21
	v_permlane32_swap_b32_e32 v18, v22
	v_permlane32_swap_b32_e32 v19, v23
	v_permlane32_swap_b32_e32 v24, v28
	v_permlane32_swap_b32_e32 v25, v29
	v_permlane32_swap_b32_e32 v26, v30
	v_permlane32_swap_b32_e32 v27, v31
	v_permlane32_swap_b32_e32 v0, v4
	v_permlane32_swap_b32_e32 v1, v5
	v_permlane32_swap_b32_e32 v2, v6
	v_permlane32_swap_b32_e32 v3, v7
	v_permlane32_swap_b32_e32 v8, v12
	v_permlane32_swap_b32_e32 v9, v13
	v_permlane32_swap_b32_e32 v10, v14
	v_permlane32_swap_b32_e32 v11, v15
	s_waitcnt lgkmcnt(3)
	v_mfma_f32_16x16x32_bf16 v[80:83], v[144:147], v[236:239], v[80:83]
	v_mfma_f32_16x16x32_bf16 v[88:91], v[148:151], v[236:239], v[88:91]
	s_waitcnt lgkmcnt(2)
	v_mfma_f32_16x16x32_bf16 v[84:87], v[144:147], v[240:243], v[84:87]
	v_mfma_f32_16x16x32_bf16 v[92:95], v[148:151], v[240:243], v[92:95]
	v_permlane16_swap_b32_e32 v112, v116
	v_permlane16_swap_b32_e32 v113, v117
	v_permlane16_swap_b32_e32 v114, v118
	v_permlane16_swap_b32_e32 v115, v119
	v_permlane16_swap_b32_e32 v120, v124
	v_permlane16_swap_b32_e32 v121, v125
	v_permlane16_swap_b32_e32 v122, v126
	v_permlane16_swap_b32_e32 v123, v127
	v_permlane16_swap_b32_e32 v96, v100
	v_permlane16_swap_b32_e32 v97, v101
	v_permlane16_swap_b32_e32 v98, v102
	v_permlane16_swap_b32_e32 v99, v103
	v_permlane16_swap_b32_e32 v104, v108
	v_permlane16_swap_b32_e32 v105, v109
	v_permlane16_swap_b32_e32 v106, v110
	v_permlane16_swap_b32_e32 v107, v111
	v_permlane32_swap_b32_e32 v112, v116
	v_permlane32_swap_b32_e32 v113, v117
	v_permlane32_swap_b32_e32 v114, v118
	v_permlane32_swap_b32_e32 v115, v119
	v_permlane32_swap_b32_e32 v120, v124
	v_permlane32_swap_b32_e32 v121, v125
	v_permlane32_swap_b32_e32 v122, v126
	v_permlane32_swap_b32_e32 v123, v127
	v_permlane32_swap_b32_e32 v96, v100
	v_permlane32_swap_b32_e32 v97, v101
	v_permlane32_swap_b32_e32 v98, v102
	v_permlane32_swap_b32_e32 v99, v103
	v_permlane32_swap_b32_e32 v104, v108
	v_permlane32_swap_b32_e32 v105, v109
	v_permlane32_swap_b32_e32 v106, v110
	v_permlane32_swap_b32_e32 v107, v111
	s_waitcnt lgkmcnt(1)
	v_mfma_f32_16x16x32_bf16 v[64:67], v[144:147], v[244:247], v[64:67]
	v_mfma_f32_16x16x32_bf16 v[72:75], v[148:151], v[244:247], v[72:75]
	s_waitcnt lgkmcnt(0)
	v_mfma_f32_16x16x32_bf16 v[68:71], v[144:147], v[248:251], v[68:71]
	v_mfma_f32_16x16x32_bf16 v[76:79], v[148:151], v[248:251], v[76:79]
	v_permlane16_swap_b32_e32 v80, v84
	v_permlane16_swap_b32_e32 v81, v85
	v_permlane16_swap_b32_e32 v82, v86
	v_permlane16_swap_b32_e32 v83, v87
	v_permlane16_swap_b32_e32 v88, v92
	v_permlane16_swap_b32_e32 v89, v93
	v_permlane16_swap_b32_e32 v90, v94
	v_permlane16_swap_b32_e32 v91, v95
	v_permlane16_swap_b32_e32 v48, v52
	v_permlane16_swap_b32_e32 v49, v53
	v_permlane16_swap_b32_e32 v50, v54
	v_permlane16_swap_b32_e32 v51, v55
	v_permlane16_swap_b32_e32 v56, v60
	v_permlane16_swap_b32_e32 v57, v61
	v_permlane16_swap_b32_e32 v58, v62
	v_permlane16_swap_b32_e32 v59, v63
	v_permlane32_swap_b32_e32 v80, v84
	v_permlane32_swap_b32_e32 v81, v85
	v_permlane32_swap_b32_e32 v82, v86
	v_permlane32_swap_b32_e32 v83, v87
	v_permlane32_swap_b32_e32 v88, v92
	v_permlane32_swap_b32_e32 v89, v93
	v_permlane32_swap_b32_e32 v90, v94
	v_permlane32_swap_b32_e32 v91, v95
	v_permlane32_swap_b32_e32 v48, v52
	v_permlane32_swap_b32_e32 v49, v53
	v_permlane32_swap_b32_e32 v50, v54
	v_permlane32_swap_b32_e32 v51, v55
	v_permlane32_swap_b32_e32 v56, v60
	v_permlane32_swap_b32_e32 v57, v61
	v_permlane32_swap_b32_e32 v58, v62
	v_permlane32_swap_b32_e32 v59, v63
	s_barrier
	s_nop 7
	v_permlane16_swap_b32_e32 v64, v68
	v_permlane16_swap_b32_e32 v65, v69
	v_permlane16_swap_b32_e32 v66, v70
	v_permlane16_swap_b32_e32 v67, v71
	v_permlane16_swap_b32_e32 v72, v76
	v_permlane16_swap_b32_e32 v73, v77
	v_permlane16_swap_b32_e32 v74, v78
	v_permlane16_swap_b32_e32 v75, v79
	v_permlane16_swap_b32_e32 v32, v36
	v_permlane16_swap_b32_e32 v33, v37
	v_permlane16_swap_b32_e32 v34, v38
	v_permlane16_swap_b32_e32 v35, v39
	v_permlane16_swap_b32_e32 v40, v44
	v_permlane16_swap_b32_e32 v41, v45
	v_permlane16_swap_b32_e32 v42, v46
	v_permlane16_swap_b32_e32 v43, v47
	v_permlane32_swap_b32_e32 v64, v68
	v_permlane32_swap_b32_e32 v65, v69
	v_permlane32_swap_b32_e32 v66, v70
	v_permlane32_swap_b32_e32 v67, v71
	v_permlane32_swap_b32_e32 v72, v76
	v_permlane32_swap_b32_e32 v73, v77
	v_permlane32_swap_b32_e32 v74, v78
	v_permlane32_swap_b32_e32 v75, v79
	v_permlane32_swap_b32_e32 v32, v36
	v_permlane32_swap_b32_e32 v33, v37
	v_permlane32_swap_b32_e32 v34, v38
	v_permlane32_swap_b32_e32 v35, v39
	v_permlane32_swap_b32_e32 v40, v44
	v_permlane32_swap_b32_e32 v41, v45
	v_permlane32_swap_b32_e32 v42, v46
	v_permlane32_swap_b32_e32 v43, v47
	s_waitcnt vmcnt(0)
	s_waitcnt vmcnt(0)
	v_and_b32_e32 v128, 63, v179
	v_lshrrev_b32_e32 v129, 6, v179
	s_lshl_b32 s20, s2, 8
	s_lshl_b32 s21, s101, 5
	s_add_i32 s20, s20, s21
	s_cmp_eq_u32 s0, 23
	s_cbranch_scc1 .Lpe_projh_ab
	v_readlane_b32 s14, v254, 15
	v_readlane_b32 s15, v254, 16
	v_readlane_b32 s16, v254, 17
	v_readlane_b32 s17, v254, 18
	s_movk_i32 s22, 0x900
	s_movk_i32 s23, 0x300
	s_cmp_lt_u32 s0, 20
	s_cselect_b32 s14, s14, s16
	s_cselect_b32 s15, s15, s17
	s_cselect_b32 s18, s22, s23
	s_movk_i32 s22, 0xf500
	s_movk_i32 s23, 0xec00
	s_cselect_b32 s19, s22, s23
	s_movk_i32 s22, 0xb00
	s_cmp_lt_u32 s0, 11
	s_cselect_b32 s14, s66, s14
	s_cselect_b32 s15, s67, s15
	s_cselect_b32 s18, s22, s18
	s_cselect_b32 s19, 0, s19
	s_mul_hi_u32 s21, s20, s18
	s_mul_i32 s20, s20, s18
	s_lshl_b32 s22, s0, 8
	s_add_i32 s22, s22, s19
	s_add_u32 s12, s14, s20
	s_addc_u32 s13, s15, s21
	s_add_u32 s12, s12, s22
	s_addc_u32 s13, s13, 0
	v_mul_u32_u24_e32 v188, 0x2400, v129
	v_lshrrev_b32_e32 v189, 5, v128
	v_mul_u32_u24_e32 v189, 0x240, v189
	v_add_u32_e32 v130, v188, v189
	v_and_b32_e32 v189, 31, v128
	v_lshl_add_u32 v130, v189, 1, v130
	v_lshrrev_b32_e32 v189, 3, v128
	v_mul_u32_u24_e32 v132, 0x90, v189
	v_add_u32_e32 v131, v188, v132
	v_and_b32_e32 v188, 7, v128
	v_lshlrev_b32_e32 v188, 4, v188
	v_add_u32_e32 v131, v131, v188
	v_lshl_add_u32 v189, v129, 6, v189
	v_add_u32_e32 v132, 0, v189
	v_add_u32_e32 v133, 8, v189
	v_add_u32_e32 v134, 16, v189
	v_add_u32_e32 v135, 24, v189
	v_mul_lo_u32 v132, v132, s18
	v_mul_lo_u32 v133, v133, s18
	v_mul_lo_u32 v134, v134, s18
	v_mul_lo_u32 v135, v135, s18
	v_add_u32_e32 v132, v132, v188
	v_add_u32_e32 v133, v133, v188
	v_add_u32_e32 v134, v134, v188
	v_add_u32_e32 v135, v135, v188
	v_cvt_pk_bf16_f32 v140, v16, v16
	v_cvt_pk_bf16_f32 v141, v112, v112
	v_cvt_pk_bf16_f32 v142, v17, v17
	v_cvt_pk_bf16_f32 v143, v113, v113
	v_cvt_pk_bf16_f32 v144, v18, v18
	v_cvt_pk_bf16_f32 v145, v114, v114
	v_cvt_pk_bf16_f32 v146, v19, v19
	v_cvt_pk_bf16_f32 v147, v115, v115
	ds_write_b16 v130, v140
	ds_write_b16 v130, v141 offset:64
	ds_write_b16 v130, v142 offset:144
	ds_write_b16 v130, v143 offset:208
	ds_write_b16 v130, v144 offset:288
	ds_write_b16 v130, v145 offset:352
	ds_write_b16 v130, v146 offset:432
	ds_write_b16 v130, v147 offset:496
	v_cvt_pk_bf16_f32 v140, v20, v20
	v_cvt_pk_bf16_f32 v141, v116, v116
	v_cvt_pk_bf16_f32 v142, v21, v21
	v_cvt_pk_bf16_f32 v143, v117, v117
	v_cvt_pk_bf16_f32 v144, v22, v22
	v_cvt_pk_bf16_f32 v145, v118, v118
	v_cvt_pk_bf16_f32 v146, v23, v23
	v_cvt_pk_bf16_f32 v147, v119, v119
	ds_write_b16 v130, v140 offset:1152
	ds_write_b16 v130, v141 offset:1216
	ds_write_b16 v130, v142 offset:1296
	ds_write_b16 v130, v143 offset:1360
	ds_write_b16 v130, v144 offset:1440
	ds_write_b16 v130, v145 offset:1504
	ds_write_b16 v130, v146 offset:1584
	ds_write_b16 v130, v147 offset:1648
	v_cvt_pk_bf16_f32 v140, v24, v24
	v_cvt_pk_bf16_f32 v141, v120, v120
	v_cvt_pk_bf16_f32 v142, v25, v25
	v_cvt_pk_bf16_f32 v143, v121, v121
	v_cvt_pk_bf16_f32 v144, v26, v26
	v_cvt_pk_bf16_f32 v145, v122, v122
	v_cvt_pk_bf16_f32 v146, v27, v27
	v_cvt_pk_bf16_f32 v147, v123, v123
	ds_write_b16 v130, v140 offset:2304
	ds_write_b16 v130, v141 offset:2368
	ds_write_b16 v130, v142 offset:2448
	ds_write_b16 v130, v143 offset:2512
	ds_write_b16 v130, v144 offset:2592
	ds_write_b16 v130, v145 offset:2656
	ds_write_b16 v130, v146 offset:2736
	ds_write_b16 v130, v147 offset:2800
	v_cvt_pk_bf16_f32 v140, v28, v28
	v_cvt_pk_bf16_f32 v141, v124, v124
	v_cvt_pk_bf16_f32 v142, v29, v29
	v_cvt_pk_bf16_f32 v143, v125, v125
	v_cvt_pk_bf16_f32 v144, v30, v30
	v_cvt_pk_bf16_f32 v145, v126, v126
	v_cvt_pk_bf16_f32 v146, v31, v31
	v_cvt_pk_bf16_f32 v147, v127, v127
	ds_write_b16 v130, v140 offset:3456
	ds_write_b16 v130, v141 offset:3520
	ds_write_b16 v130, v142 offset:3600
	ds_write_b16 v130, v143 offset:3664
	ds_write_b16 v130, v144 offset:3744
	ds_write_b16 v130, v145 offset:3808
	ds_write_b16 v130, v146 offset:3888
	ds_write_b16 v130, v147 offset:3952
	s_waitcnt lgkmcnt(0)
	ds_read_b128 v[148:151], v131
	ds_read_b128 v[152:155], v131 offset:1152
	ds_read_b128 v[156:159], v131 offset:2304
	ds_read_b128 v[160:163], v131 offset:3456
	s_waitcnt lgkmcnt(3)
	global_store_dwordx4 v132, v[148:151], s[12:13]
	s_waitcnt lgkmcnt(2)
	global_store_dwordx4 v133, v[152:155], s[12:13]
	s_waitcnt lgkmcnt(1)
	global_store_dwordx4 v134, v[156:159], s[12:13]
	s_waitcnt lgkmcnt(0)
	global_store_dwordx4 v135, v[160:163], s[12:13]
	v_cvt_pk_bf16_f32 v140, v80, v80
	v_cvt_pk_bf16_f32 v141, v64, v64
	v_cvt_pk_bf16_f32 v142, v81, v81
	v_cvt_pk_bf16_f32 v143, v65, v65
	v_cvt_pk_bf16_f32 v144, v82, v82
	v_cvt_pk_bf16_f32 v145, v66, v66
	v_cvt_pk_bf16_f32 v146, v83, v83
	v_cvt_pk_bf16_f32 v147, v67, v67
	ds_write_b16 v130, v140
	ds_write_b16 v130, v141 offset:64
	ds_write_b16 v130, v142 offset:144
	ds_write_b16 v130, v143 offset:208
	ds_write_b16 v130, v144 offset:288
	ds_write_b16 v130, v145 offset:352
	ds_write_b16 v130, v146 offset:432
	ds_write_b16 v130, v147 offset:496
	v_cvt_pk_bf16_f32 v140, v84, v84
	v_cvt_pk_bf16_f32 v141, v68, v68
	v_cvt_pk_bf16_f32 v142, v85, v85
	v_cvt_pk_bf16_f32 v143, v69, v69
	v_cvt_pk_bf16_f32 v144, v86, v86
	v_cvt_pk_bf16_f32 v145, v70, v70
	v_cvt_pk_bf16_f32 v146, v87, v87
	v_cvt_pk_bf16_f32 v147, v71, v71
	ds_write_b16 v130, v140 offset:1152
	ds_write_b16 v130, v141 offset:1216
	ds_write_b16 v130, v142 offset:1296
	ds_write_b16 v130, v143 offset:1360
	ds_write_b16 v130, v144 offset:1440
	ds_write_b16 v130, v145 offset:1504
	ds_write_b16 v130, v146 offset:1584
	ds_write_b16 v130, v147 offset:1648
	v_cvt_pk_bf16_f32 v140, v88, v88
	v_cvt_pk_bf16_f32 v141, v72, v72
	v_cvt_pk_bf16_f32 v142, v89, v89
	v_cvt_pk_bf16_f32 v143, v73, v73
	v_cvt_pk_bf16_f32 v144, v90, v90
	v_cvt_pk_bf16_f32 v145, v74, v74
	v_cvt_pk_bf16_f32 v146, v91, v91
	v_cvt_pk_bf16_f32 v147, v75, v75
	ds_write_b16 v130, v140 offset:2304
	ds_write_b16 v130, v141 offset:2368
	ds_write_b16 v130, v142 offset:2448
	ds_write_b16 v130, v143 offset:2512
	ds_write_b16 v130, v144 offset:2592
	ds_write_b16 v130, v145 offset:2656
	ds_write_b16 v130, v146 offset:2736
	ds_write_b16 v130, v147 offset:2800
	v_cvt_pk_bf16_f32 v140, v92, v92
	v_cvt_pk_bf16_f32 v141, v76, v76
	v_cvt_pk_bf16_f32 v142, v93, v93
	v_cvt_pk_bf16_f32 v143, v77, v77
	v_cvt_pk_bf16_f32 v144, v94, v94
	v_cvt_pk_bf16_f32 v145, v78, v78
	v_cvt_pk_bf16_f32 v146, v95, v95
	v_cvt_pk_bf16_f32 v147, v79, v79
	ds_write_b16 v130, v140 offset:3456
	ds_write_b16 v130, v141 offset:3520
	ds_write_b16 v130, v142 offset:3600
	ds_write_b16 v130, v143 offset:3664
	ds_write_b16 v130, v144 offset:3744
	ds_write_b16 v130, v145 offset:3808
	ds_write_b16 v130, v146 offset:3888
	ds_write_b16 v130, v147 offset:3952
	s_waitcnt lgkmcnt(0)
	ds_read_b128 v[148:151], v131
	ds_read_b128 v[152:155], v131 offset:1152
	ds_read_b128 v[156:159], v131 offset:2304
	ds_read_b128 v[160:163], v131 offset:3456
	s_waitcnt lgkmcnt(3)
	global_store_dwordx4 v132, v[148:151], s[12:13] offset:128
	s_waitcnt lgkmcnt(2)
	global_store_dwordx4 v133, v[152:155], s[12:13] offset:128
	s_waitcnt lgkmcnt(1)
	global_store_dwordx4 v134, v[156:159], s[12:13] offset:128
	s_waitcnt lgkmcnt(0)
	global_store_dwordx4 v135, v[160:163], s[12:13] offset:128
	s_branch .Lpe_projh_end
.Lpe_projh_ab:
	v_readlane_b32 s14, v254, 19
	v_readlane_b32 s15, v254, 20
	s_mul_i32 s20, s20, 0x60
	s_add_u32 s12, s14, s20
	s_addc_u32 s13, s15, 0
	v_lshrrev_b32_e32 v189, 5, v128
	v_lshlrev_b32_e32 v189, 2, v189
	v_lshl_add_u32 v189, v129, 6, v189
	v_mul_u32_u24_e32 v189, 0x60, v189
	v_and_b32_e32 v188, 31, v128
	v_lshl_add_u32 v189, v188, 2, v189
	v_cmp_gt_u32_e32 vcc, 24, v188
	s_and_saveexec_b64 s[14:15], vcc
	global_store_dword v189, v16, s[12:13]
	global_store_dword v189, v17, s[12:13] offset:96
	global_store_dword v189, v18, s[12:13] offset:192
	global_store_dword v189, v19, s[12:13] offset:288
	global_store_dword v189, v20, s[12:13] offset:768
	global_store_dword v189, v21, s[12:13] offset:864
	global_store_dword v189, v22, s[12:13] offset:960
	global_store_dword v189, v23, s[12:13] offset:1056
	global_store_dword v189, v24, s[12:13] offset:1536
	global_store_dword v189, v25, s[12:13] offset:1632
	global_store_dword v189, v26, s[12:13] offset:1728
	global_store_dword v189, v27, s[12:13] offset:1824
	global_store_dword v189, v28, s[12:13] offset:2304
	global_store_dword v189, v29, s[12:13] offset:2400
	global_store_dword v189, v30, s[12:13] offset:2496
	global_store_dword v189, v31, s[12:13] offset:2592
	s_mov_b64 exec, s[14:15]
.Lpe_projh_end:
	s_mov_b32 s100, 0
	s_barrier
	s_branch .LBB0_350
